# add: retention prompt units stage Q/K row pieces so each thread's 8 loads hit one 128-byte line (LDS images unchanged)
# speedup vs baseline: 1.0079x; 1.0017x over previous
.LBB0_664:
	s_cmp_lt_i32 s80, 4
	s_cselect_b64 s[2:3], -1, 0
	s_and_b64 s[56:57], s[2:3], s[0:1]
	s_andn2_b64 vcc, exec, s[56:57]
	s_cbranch_vccnz .LBB0_820
	s_ashr_i32 s60, s33, 1
	s_cmp_lt_i32 s88, s60
	s_mov_b64 s[0:1], -1
	s_cbranch_scc1 .LBB0_763
	v_writelane_b32 v244, s62, 0
	s_sub_i32 s4, s88, s60
	s_sub_i32 s76, s33, s60
	v_writelane_b32 v244, s63, 1
	v_writelane_b32 v244, s61, 2
	v_writelane_b32 v244, s90, 3
	s_bitcmp0_b32 s82, 1
	s_mov_b32 s94, s84
	v_writelane_b32 v244, s91, 4
	s_cselect_b64 s[0:1], -1, 0
	s_cmpk_gt_i32 s4, 0x7f
	v_writelane_b32 v245, s56, 60
	v_writelane_b32 v244, s94, 5
	s_cselect_b64 s[2:3], -1, 0
	v_writelane_b32 v245, s57, 61
	v_writelane_b32 v244, s95, 6
	s_or_b64 s[0:1], s[0:1], s[2:3]
	v_writelane_b32 v245, s96, 62
	v_writelane_b32 v244, s88, 7
	s_mov_b32 s81, 0
	s_mov_b32 s92, s4
	s_and_b64 vcc, exec, s[0:1]
	v_lshrrev_b32_e32 v144, 6, v208
	v_lshrrev_b32_e32 v125, 7, v208
	v_writelane_b32 v245, s97, 63
	v_writelane_b32 v244, s60, 8
	s_cbranch_vccnz .LBB0_722
	v_readlane_b32 s0, v245, 62
	v_readlane_b32 s1, v245, 63
	s_add_u32 s84, s0, 0xa200000
	s_addc_u32 s85, s1, 0
	s_add_u32 s93, s0, 0x19340000
	s_addc_u32 s0, s1, 0
	v_writelane_b32 v244, s0, 9
	v_readlane_b32 s0, v245, 0
	v_readlane_b32 s2, v245, 2
	v_readlane_b32 s3, v245, 3
	s_add_u32 s94, s2, 0x450d200
	v_bfe_u32 v1, v208, 4, 2
	s_addc_u32 s95, s3, 0
	v_and_b32_e32 v7, 0x3c0, v208
	v_lshlrev_b32_e32 v9, 3, v1
	s_add_i32 s3, 0, 0x19000
	v_add3_u32 v146, s3, v7, v9
	s_movk_i32 s3, 0x7f
	v_bitop3_b32 v148, v208, s3, v208 bitop3:0x3f
	s_add_i32 s3, 0, 0x21800
	v_readlane_b32 s1, v245, 1
	s_movk_i32 s74, 0x880
	v_mov_b32_e32 v7, s3
	s_add_i32 s1, 0, 0x10800
	v_mad_u32_u24 v20, v125, s74, v7
	v_mov_b32_e32 v7, 0x220
	v_and_b32_e32 v145, 0x7f, v208
	v_mov_b32_e32 v0, 0
	s_movk_i32 s0, 0x210
	v_mov_b32_e32 v5, s1
	v_mad_u32_u24 v149, v125, s74, v7
	v_mov_b32_e32 v7, 0x440
	v_lshlrev_b32_e32 v4, 4, v125
	v_mad_u32_u24 v13, v145, s0, v5
	v_and_b32_e32 v6, 14, v144
	v_lshlrev_b32_e32 v8, 2, v144
	s_movk_i32 s2, 0x2100
	v_mov_b32_e32 v5, v0
	v_mad_u32_u24 v151, v125, s74, v7
	v_mov_b32_e32 v7, 0x660
	v_mad_u32_u24 v16, v6, s2, 0
	v_lshl_add_u64 v[122:123], s[84:85], 0, v[4:5]
	v_lshlrev_b32_e32 v5, 2, v1
	v_lshlrev_b32_e32 v9, 4, v144
	v_mad_u32_u24 v152, v125, s74, v7
	v_lshlrev_b32_e32 v12, 4, v6
	v_and_b32_e32 v7, 15, v208
	v_and_b32_e32 v6, 4, v8
	v_or_b32_e32 v147, v5, v9
	v_lshlrev_b32_e32 v8, 4, v6
	v_or_b32_e32 v9, v7, v9
	v_or_b32_e32 v9, 16, v9
	v_or_b32_e32 v8, v8, v5
	v_sub_u32_e32 v10, v9, v8
	v_cvt_f32_i32_e32 v157, v10
	v_pk_mov_b32 v[10:11], v[6:7], v[8:9] op_sel:[1,0]
	v_mul_u32_u24_e32 v24, 0x2100, v6
	v_or_b32_e32 v10, v12, v10
	v_or_b32_e32 v5, 3, v8
	v_or_b32_e32 v25, v12, v7
	v_or_b32_e32 v26, 16, v8
	v_or_b32_e32 v6, 19, v11
	v_sub_co_u32_e64 v11, s[16:17], v10, v8
	v_cmp_gt_u32_e64 s[14:15], v5, v9
	v_cvt_f32_i32_e32 v159, v11
	v_cmp_lt_u32_e64 s[20:21], v10, v5
	v_or_b32_e32 v5, 18, v8
	v_sub_u32_e32 v11, v10, v26
	v_cmp_gt_u32_e64 s[28:29], v6, v25
	v_cmp_gt_u32_e64 s[38:39], v6, v9
	v_or_b32_e32 v6, 32, v8
	v_cvt_f32_i32_e32 v162, v11
	v_cmp_lt_u32_e64 s[24:25], v10, v5
	v_sub_u32_e32 v11, v9, v26
	v_cmp_lt_u32_e64 s[34:35], v9, v5
	v_or_b32_e32 v5, 34, v8
	v_sub_u32_e32 v12, v10, v6
	v_or_b32_e32 v14, 2, v8
	v_lshl_add_u32 v156, v8, 1, s1
	v_cmp_lt_u32_e64 s[8:9], v9, v8
	v_cmp_gt_u32_e64 s[12:13], v9, v8
	v_cmp_gt_u32_e64 s[18:19], v10, v8
	v_cvt_f32_i32_e32 v163, v11
	v_or_b32_e32 v11, 35, v8
	v_lshl_add_u32 v164, v6, 1, s1
	v_cvt_f32_i32_e32 v165, v12
	v_cmp_lt_u32_e64 s[42:43], v10, v5
	v_cmp_lt_u32_e64 s[44:45], v10, v6
	v_cmp_gt_u32_e64 s[46:47], v10, v6
	v_sub_u32_e32 v12, v9, v6
	v_cmp_lt_u32_e64 s[50:51], v9, v5
	v_cmp_lt_u32_e64 s[52:53], v9, v6
	v_cmp_gt_u32_e64 s[56:57], v9, v6
	v_or_b32_e32 v5, 50, v8
	v_or_b32_e32 v6, 48, v8
	v_or_b32_e32 v8, 51, v8
	v_lshlrev_b32_e32 v17, 4, v1
	v_mul_u32_u24_e32 v153, 0x210, v7
	v_cmp_lt_u32_e64 s[22:23], v10, v14
	v_mul_u32_u24_e32 v160, 0x110, v10
	v_cmp_lt_u32_e64 s[26:27], v10, v26
	v_cmp_gt_u32_e64 s[30:31], v10, v26
	v_cmp_gt_u32_e64 s[48:49], v11, v10
	v_cmp_gt_u32_e64 s[54:55], v11, v9
	v_lshl_add_u32 v167, v6, 1, s1
	v_sub_u32_e32 v11, v10, v6
	v_cmp_lt_u32_e64 s[58:59], v10, v5
	v_cmp_lt_u32_e64 s[60:61], v10, v6
	v_cmp_gt_u32_e64 s[62:63], v10, v6
	v_cmp_gt_u32_e64 s[64:65], v8, v10
	v_sub_u32_e32 v10, v9, v6
	v_cmp_lt_u32_e64 s[68:69], v9, v6
	v_cmp_gt_u32_e64 s[72:73], v9, v6
	v_add_u32_e32 v6, 4, v147
	v_add3_u32 v154, 0, v153, v17
	v_cvt_f32_i32_e32 v166, v12
	v_cvt_f32_i32_e32 v168, v11
	v_cvt_f32_i32_e32 v169, v10
	v_cvt_f32_u32_e32 v175, v6
	v_lshlrev_b32_e32 v6, 13, v144
	v_lshlrev_b32_e32 v15, 1, v145
	v_mad_u32_u24 v155, v144, s2, v154
	s_movk_i32 s2, 0x110
	v_cmp_lt_u32_e64 s[66:67], v9, v5
	v_or_b32_e32 v5, 16, v7
	v_lshl_or_b32 v6, v1, 10, v6
	v_mad_u32_u24 v1, v7, s0, v24
	v_lshlrev_b32_e32 v2, 3, v125
	v_mad_u32_u24 v3, v145, s0, 0
	v_mul_u32_u24_e32 v18, 0x1100, v144
	v_mul_u32_u24_e32 v19, 0x2200, v144
	v_add_u32_e32 v21, s3, v149
	v_add_u32_e32 v22, s3, v151
	v_add_u32_e32 v23, s3, v152
	v_cmp_lt_u32_e64 s[10:11], v9, v14
	v_mul_lo_u32 v158, v9, s2
	v_cmp_lt_u32_e64 s[36:37], v9, v26
	v_cmp_gt_u32_e64 s[40:41], v9, v26
	v_cmp_gt_u32_e64 s[70:71], v8, v9
	v_mul_u32_u24_e32 v5, 0x210, v5
	v_mov_b32_e32 v124, v7
	v_or_b32_e32 v170, 1, v147
	v_or_b32_e32 v172, 2, v147
	v_or_b32_e32 v173, 3, v147
	v_add_u32_e32 v176, s1, v15
	v_add_u32_e32 v9, s1, v149
	v_add_u32_e32 v11, s1, v151
	v_add_u32_e32 v25, s1, v152
	v_or_b32_e32 v8, 0x1000, v6
	v_or_b32_e32 v10, 0x1100, v6
	v_or_b32_e32 v12, 0x1200, v6
	v_or_b32_e32 v14, 0x1300, v6
	v_add3_u32 v181, v1, v17, 0
	v_mad_u32_u24 v1, v7, s2, v17
	v_cmp_gt_u32_e64 s[4:5], 16, v145
	v_cmp_lt_u32_e64 s[6:7], 15, v145
	v_add_u32_e32 v150, s3, v15
	v_lshl_add_u32 v161, v26, 1, s1
	v_cvt_f32_ubyte0_e32 v171, v170
	v_cvt_f32_ubyte0_e32 v174, v173
	v_mad_u32_u24 v177, v125, s74, v176
	v_cvt_f32_ubyte0_e32 v178, v172
	v_add3_u32 v180, v16, v17, v153
	v_add_u32_e32 v182, 0, v1
	v_add3_u32 v183, v1, v18, 0
	v_add3_u32 v184, v1, v19, 0
	v_lshlrev_b32_e32 v126, 1, v2
	v_lshlrev_b32_e32 v128, 2, v124
	v_add_u32_e32 v185, v3, v4
	v_add_u32_e32 v186, v13, v4
	v_add_u32_e32 v187, v20, v15
	v_add_u32_e32 v188, v21, v15
	v_add_u32_e32 v189, v22, v15
	v_add_u32_e32 v190, v23, v15
	s_mov_b32 s96, 0xc2fc0000
	s_movk_i32 s3, 0x7fff
	s_mov_b32 s88, 0xffff0000
	v_add_u32_e32 v191, v146, v5
	v_add_u32_e32 v192, v9, v15
	v_add_u32_e32 v193, v11, v15
	v_add_u32_e32 v194, v25, v15
	v_lshlrev_b32_e32 v130, 2, v6
	v_lshlrev_b32_e32 v132, 2, v8
	v_lshlrev_b32_e32 v134, 2, v10
	v_lshlrev_b32_e32 v136, 2, v12
	v_lshlrev_b32_e32 v138, 2, v14
	v_mov_b32_e32 v195, 0xbbb906ce
	v_mov_b32_e32 v196, 0xbc3963dd
	v_not_b32_e32 v197, 63
	v_mov_b32_e32 v198, 0x42800000
	v_mov_b32_e32 v199, 1
	v_mul_u32_u24_e32 v214, 0x70, v125
	v_mov_b32_e32 v215, 0
	v_add_u32_e32 v216, v185, v214
	v_add_u32_e32 v217, v186, v214
	v_mul_u32_u24_e32 v218, 0x3b80, v125
	v_add_u32_e32 v218, v177, v218
	s_mov_b32 s89, s92
	s_branch .LBB0_669

.LBB0_674:
	s_ashr_i32 s77, s89, 5
	s_mul_i32 s91, s77, 0x810
	v_add_u32_e32 v68, s91, v145
	v_ashrrev_i32_e32 v69, 31, v68
	v_lshlrev_b64 v[2:3], 13, v[68:69]
	v_lshl_add_u64 v[2:3], s[84:85], 0, v[2:3]
	s_lshl_b32 s80, s90, 9
	v_lshl_add_u64 v[2:3], v[2:3], 0, s[80:81]
	v_mov_b32_e32 v127, v0
	v_lshl_add_u64 v[70:71], v[2:3], 0, v[126:127]
	v_lshl_add_u64 v[220:221], v[70:71], 0, v[214:215]
	v_mov_b32_e32 v2, v0
	v_mov_b32_e32 v3, v0
	v_mov_b32_e32 v1, v0
	v_mov_b64_e32 v[6:7], v[2:3]
	s_waitcnt vmcnt(0)
	v_mov_b64_e32 v[10:11], v[2:3]
	v_mov_b64_e32 v[4:5], v[0:1]
	v_mov_b64_e32 v[8:9], v[0:1]
	s_and_saveexec_b64 s[0:1], s[4:5]
	s_cbranch_execz .LBB0_676
	global_load_dwordx4 v[4:7], v[220:221], off
	global_load_dwordx4 v[8:11], v[220:221], off offset:2048
.LBB0_676:
	s_or_b64 exec, exec, s[0:1]
	v_mov_b64_e32 v[14:15], v[2:3]
	v_mov_b64_e32 v[18:19], v[2:3]
	v_mov_b64_e32 v[12:13], v[0:1]
	v_mov_b64_e32 v[16:17], v[0:1]
	s_and_saveexec_b64 s[0:1], s[4:5]
	s_cbranch_execz .LBB0_678
	global_load_dwordx4 v[12:15], v[220:221], off offset:16
	global_load_dwordx4 v[16:19], v[220:221], off offset:2064
.LBB0_678:
	s_or_b64 exec, exec, s[0:1]
	v_mov_b32_e32 v2, v0
	v_mov_b32_e32 v3, v0
	v_mov_b32_e32 v1, v0
	v_mov_b64_e32 v[22:23], v[2:3]
	v_mov_b64_e32 v[26:27], v[2:3]
	v_mov_b64_e32 v[20:21], v[0:1]
	v_mov_b64_e32 v[24:25], v[0:1]
	s_and_saveexec_b64 s[0:1], s[4:5]
	s_cbranch_execz .LBB0_680
	global_load_dwordx4 v[20:23], v[220:221], off offset:32
	global_load_dwordx4 v[24:27], v[220:221], off offset:2080
.LBB0_680:
	s_or_b64 exec, exec, s[0:1]
	v_mov_b64_e32 v[30:31], v[2:3]
	v_mov_b64_e32 v[34:35], v[2:3]
	v_mov_b64_e32 v[28:29], v[0:1]
	v_mov_b64_e32 v[32:33], v[0:1]
	s_and_saveexec_b64 s[0:1], s[4:5]
	s_cbranch_execz .LBB0_682
	global_load_dwordx4 v[28:31], v[220:221], off offset:48
	global_load_dwordx4 v[32:35], v[220:221], off offset:2096
.LBB0_682:
	s_or_b64 exec, exec, s[0:1]
	v_mov_b32_e32 v2, v0
	v_mov_b32_e32 v3, v0
	v_mov_b32_e32 v1, v0
	v_mov_b64_e32 v[38:39], v[2:3]
	v_mov_b64_e32 v[42:43], v[2:3]
	v_mov_b64_e32 v[36:37], v[0:1]
	v_mov_b64_e32 v[40:41], v[0:1]
	s_and_saveexec_b64 s[0:1], s[4:5]
	s_cbranch_execz .LBB0_684
	global_load_dwordx4 v[36:39], v[220:221], off offset:64
	global_load_dwordx4 v[40:43], v[220:221], off offset:2112
.LBB0_684:
	s_or_b64 exec, exec, s[0:1]
	v_mov_b64_e32 v[46:47], v[2:3]
	v_mov_b64_e32 v[50:51], v[2:3]
	v_mov_b64_e32 v[44:45], v[0:1]
	v_mov_b64_e32 v[48:49], v[0:1]
	s_and_saveexec_b64 s[0:1], s[4:5]
	s_cbranch_execz .LBB0_686
	global_load_dwordx4 v[44:47], v[220:221], off offset:80
	global_load_dwordx4 v[48:51], v[220:221], off offset:2128
.LBB0_686:
	s_or_b64 exec, exec, s[0:1]
	v_mov_b32_e32 v2, v0
	v_mov_b32_e32 v3, v0
	v_mov_b32_e32 v1, v0
	v_mov_b64_e32 v[54:55], v[2:3]
	v_mov_b64_e32 v[58:59], v[2:3]
	v_mov_b64_e32 v[52:53], v[0:1]
	v_mov_b64_e32 v[56:57], v[0:1]
	s_and_saveexec_b64 s[0:1], s[4:5]
	s_cbranch_execz .LBB0_688
	global_load_dwordx4 v[52:55], v[220:221], off offset:96
	global_load_dwordx4 v[56:59], v[220:221], off offset:2144
.LBB0_688:
	s_or_b64 exec, exec, s[0:1]
	v_mov_b64_e32 v[62:63], v[2:3]
	v_mov_b64_e32 v[66:67], v[2:3]
	v_mov_b64_e32 v[60:61], v[0:1]
	v_mov_b64_e32 v[64:65], v[0:1]
	s_and_saveexec_b64 s[0:1], s[4:5]
	s_cbranch_execz .LBB0_690
	global_load_dwordx4 v[60:63], v[220:221], off offset:112
	global_load_dwordx4 v[64:67], v[220:221], off offset:2160

.LBB0_695:
	v_add_u32_e32 v88, v150, v149
	s_waitcnt vmcnt(0)
	ds_write_b128 v216, v[4:7]
	ds_write_b128 v217, v[8:11]
	ds_write_b128 v216, v[12:15] offset:16
	ds_write_b128 v217, v[16:19] offset:16
	ds_write_b128 v216, v[20:23] offset:32
	ds_write_b128 v217, v[24:27] offset:32
	ds_write_b128 v216, v[28:31] offset:48
	ds_write_b128 v217, v[32:35] offset:48
	ds_write_b128 v216, v[36:39] offset:64
	ds_write_b128 v217, v[40:43] offset:64
	ds_write_b128 v216, v[44:47] offset:80
	ds_write_b128 v217, v[48:51] offset:80
	ds_write_b128 v216, v[52:55] offset:96
	ds_write_b128 v217, v[56:59] offset:96
	ds_write_b128 v216, v[60:63] offset:112
	ds_write_b128 v217, v[64:67] offset:112
	ds_write_b16 v187, v72
	ds_write_b16_d16_hi v187, v72 offset:272
	ds_write_b16 v88, v73
	ds_write_b16_d16_hi v188, v73 offset:272
	v_add_u32_e32 v88, v150, v151
	ds_write_b16 v88, v74
	ds_write_b16_d16_hi v189, v74 offset:272
	v_add_u32_e32 v88, v150, v152
	s_mov_b32 s0, 0
	v_mov_b32_e32 v90, 0
	v_mov_b32_e32 v91, v129
	v_mov_b32_e32 v92, v129
	v_mov_b32_e32 v93, v129
	v_mov_b32_e32 v94, 0
	v_mov_b32_e32 v95, v129
	v_mov_b32_e32 v96, v129
	v_mov_b32_e32 v97, v129
	v_mov_b32_e32 v98, 0
	v_mov_b32_e32 v99, v129
	v_mov_b32_e32 v100, v129
	v_mov_b32_e32 v101, v129
	v_mov_b32_e32 v102, 0
	v_mov_b32_e32 v103, v129
	v_mov_b32_e32 v104, v129
	v_mov_b32_e32 v105, v129
	v_mov_b32_e32 v106, 0
	v_mov_b32_e32 v107, v129
	v_mov_b32_e32 v108, v129
	v_mov_b32_e32 v109, v129
	v_mov_b32_e32 v110, 0
	v_mov_b32_e32 v111, v129
	v_mov_b32_e32 v112, v129
	v_mov_b32_e32 v113, v129
	v_mov_b32_e32 v114, 0
	v_mov_b32_e32 v115, v129
	v_mov_b32_e32 v116, v129
	v_mov_b32_e32 v117, v129
	v_mov_b32_e32 v118, 0
	v_mov_b32_e32 v119, v129
	v_mov_b32_e32 v120, v129
	v_mov_b32_e32 v121, v129
	ds_write_b16 v88, v75
	ds_write_b16_d16_hi v190, v75 offset:272
	s_waitcnt lgkmcnt(0)
	s_barrier

.LBB0_713:
	s_or_b64 exec, exec, s[0:1]
	v_add_u32_e32 v88, s2, v148
	v_cvt_f32_i32_e32 v88, v88
	s_barrier
	v_mul_f32_e32 v89, v133, v88
	v_cmp_gt_f32_e32 vcc, s96, v89
	s_cmp_eq_u32 s80, 16
	s_nop 0
	v_cndmask_b32_e32 v89, 0, v198, vcc
	v_fmac_f32_e32 v89, v133, v88
	v_exp_f32_e32 v88, v89
	v_cndmask_b32_e32 v89, 0, v197, vcc
	v_cmp_gt_u32_e32 vcc, s2, v145
	v_ldexp_f32 v88, v88, v89
	s_nop 0
	v_cndmask_b32_e32 v88, 0, v88, vcc
	v_lshlrev_b32_e32 v89, 16, v8
	v_mul_f32_e32 v89, v88, v89
	v_bfe_u32 v90, v89, 16, 1
	v_add3_u32 v89, v89, v90, s3
	ds_write_b16_d16_hi v218, v89
	v_and_b32_e32 v89, 0xffff0000, v8
	v_mul_f32_e32 v89, v88, v89
	v_bfe_u32 v90, v89, 16, 1
	v_add3_u32 v89, v89, v90, s3
	ds_write_b16_d16_hi v218, v89 offset:272
	v_lshlrev_b32_e32 v89, 16, v9
	v_mul_f32_e32 v89, v88, v89
	v_bfe_u32 v90, v89, 16, 1
	v_add3_u32 v89, v89, v90, s3
	v_add_u32_e32 v90, v176, v149
	ds_write_b16_d16_hi v218, v89 offset:544
	v_and_b32_e32 v89, 0xffff0000, v9
	v_mul_f32_e32 v89, v88, v89
	v_bfe_u32 v90, v89, 16, 1
	v_add3_u32 v89, v89, v90, s3
	ds_write_b16_d16_hi v218, v89 offset:816
	v_lshlrev_b32_e32 v89, 16, v10
	v_mul_f32_e32 v89, v88, v89
	v_bfe_u32 v90, v89, 16, 1
	v_add3_u32 v89, v89, v90, s3
	v_add_u32_e32 v90, v176, v151
	ds_write_b16_d16_hi v218, v89 offset:1088
	v_and_b32_e32 v89, 0xffff0000, v10
	v_mul_f32_e32 v89, v88, v89
	v_bfe_u32 v90, v89, 16, 1
	v_add3_u32 v89, v89, v90, s3
	ds_write_b16_d16_hi v218, v89 offset:1360
	v_lshlrev_b32_e32 v89, 16, v11
	v_mul_f32_e32 v89, v88, v89
	v_bfe_u32 v90, v89, 16, 1
	v_add3_u32 v89, v89, v90, s3
	v_add_u32_e32 v90, v176, v152
	ds_write_b16_d16_hi v218, v89 offset:1632
	v_and_b32_e32 v89, 0xffff0000, v11
	v_mul_f32_e32 v89, v88, v89
	v_bfe_u32 v90, v89, 16, 1
	v_add3_u32 v89, v89, v90, s3
	ds_write_b16_d16_hi v218, v89 offset:1904
	v_lshlrev_b32_e32 v89, 16, v16
	v_mul_f32_e32 v89, v88, v89
	v_bfe_u32 v90, v89, 16, 1
	v_add3_u32 v89, v89, v90, s3
	ds_write_b16_d16_hi v218, v89 offset:2176
	v_and_b32_e32 v89, 0xffff0000, v16
	v_mul_f32_e32 v89, v88, v89
	v_bfe_u32 v90, v89, 16, 1
	v_add3_u32 v89, v89, v90, s3
	ds_write_b16_d16_hi v218, v89 offset:2448
	v_lshlrev_b32_e32 v89, 16, v17
	v_mul_f32_e32 v89, v88, v89
	v_bfe_u32 v90, v89, 16, 1
	v_add3_u32 v89, v89, v90, s3
	ds_write_b16_d16_hi v218, v89 offset:2720
	v_and_b32_e32 v89, 0xffff0000, v17
	v_mul_f32_e32 v89, v88, v89
	v_bfe_u32 v90, v89, 16, 1
	v_add3_u32 v89, v89, v90, s3
	ds_write_b16_d16_hi v218, v89 offset:2992
	v_lshlrev_b32_e32 v89, 16, v18
	v_mul_f32_e32 v89, v88, v89
	v_bfe_u32 v90, v89, 16, 1
	v_add3_u32 v89, v89, v90, s3
	ds_write_b16_d16_hi v218, v89 offset:3264
	v_and_b32_e32 v89, 0xffff0000, v18
	v_mul_f32_e32 v89, v88, v89
	v_bfe_u32 v90, v89, 16, 1
	v_add3_u32 v89, v89, v90, s3
	ds_write_b16_d16_hi v218, v89 offset:3536
	v_lshlrev_b32_e32 v89, 16, v19
	v_mul_f32_e32 v89, v88, v89
	v_bfe_u32 v90, v89, 16, 1
	v_add3_u32 v89, v89, v90, s3
	ds_write_b16_d16_hi v218, v89 offset:3808
	v_and_b32_e32 v89, 0xffff0000, v19
	v_mul_f32_e32 v89, v88, v89
	v_bfe_u32 v90, v89, 16, 1
	v_add3_u32 v89, v89, v90, s3
	ds_write_b16_d16_hi v218, v89 offset:4080
	v_lshlrev_b32_e32 v89, 16, v24
	v_mul_f32_e32 v89, v88, v89
	v_bfe_u32 v90, v89, 16, 1
	v_add3_u32 v89, v89, v90, s3
	ds_write_b16_d16_hi v218, v89 offset:4352
	v_and_b32_e32 v89, 0xffff0000, v24
	v_mul_f32_e32 v89, v88, v89
	v_bfe_u32 v90, v89, 16, 1
	v_add3_u32 v89, v89, v90, s3
	ds_write_b16_d16_hi v218, v89 offset:4624
	v_lshlrev_b32_e32 v89, 16, v25
	v_mul_f32_e32 v89, v88, v89
	v_bfe_u32 v90, v89, 16, 1
	v_add3_u32 v89, v89, v90, s3
	ds_write_b16_d16_hi v218, v89 offset:4896
	v_and_b32_e32 v89, 0xffff0000, v25
	v_mul_f32_e32 v89, v88, v89
	v_bfe_u32 v90, v89, 16, 1
	v_add3_u32 v89, v89, v90, s3
	ds_write_b16_d16_hi v218, v89 offset:5168
	v_lshlrev_b32_e32 v89, 16, v26
	v_mul_f32_e32 v89, v88, v89
	v_bfe_u32 v90, v89, 16, 1
	v_add3_u32 v89, v89, v90, s3
	ds_write_b16_d16_hi v218, v89 offset:5440
	v_and_b32_e32 v89, 0xffff0000, v26
	v_mul_f32_e32 v89, v88, v89
	v_bfe_u32 v90, v89, 16, 1
	v_add3_u32 v89, v89, v90, s3
	ds_write_b16_d16_hi v218, v89 offset:5712
	v_lshlrev_b32_e32 v89, 16, v27
	v_mul_f32_e32 v89, v88, v89
	v_bfe_u32 v90, v89, 16, 1
	v_add3_u32 v89, v89, v90, s3
	ds_write_b16_d16_hi v218, v89 offset:5984
	v_and_b32_e32 v89, 0xffff0000, v27
	v_mul_f32_e32 v89, v88, v89
	v_bfe_u32 v90, v89, 16, 1
	v_add3_u32 v89, v89, v90, s3
	ds_write_b16_d16_hi v218, v89 offset:6256
	v_lshlrev_b32_e32 v89, 16, v32
	v_mul_f32_e32 v89, v88, v89
	v_bfe_u32 v90, v89, 16, 1
	v_add3_u32 v89, v89, v90, s3
	ds_write_b16_d16_hi v218, v89 offset:6528
	v_and_b32_e32 v89, 0xffff0000, v32
	v_mul_f32_e32 v89, v88, v89
	v_bfe_u32 v90, v89, 16, 1
	v_add3_u32 v89, v89, v90, s3
	ds_write_b16_d16_hi v218, v89 offset:6800
	v_lshlrev_b32_e32 v89, 16, v33
	v_mul_f32_e32 v89, v88, v89
	v_bfe_u32 v90, v89, 16, 1
	v_add3_u32 v89, v89, v90, s3
	ds_write_b16_d16_hi v218, v89 offset:7072
	v_and_b32_e32 v89, 0xffff0000, v33
	v_mul_f32_e32 v89, v88, v89
	v_bfe_u32 v90, v89, 16, 1
	v_add3_u32 v89, v89, v90, s3
	ds_write_b16_d16_hi v218, v89 offset:7344
	v_lshlrev_b32_e32 v89, 16, v34
	v_mul_f32_e32 v89, v88, v89
	v_bfe_u32 v90, v89, 16, 1
	v_add3_u32 v89, v89, v90, s3
	ds_write_b16_d16_hi v218, v89 offset:7616
	v_and_b32_e32 v89, 0xffff0000, v34
	v_mul_f32_e32 v89, v88, v89
	v_bfe_u32 v90, v89, 16, 1
	v_add3_u32 v89, v89, v90, s3
	ds_write_b16_d16_hi v218, v89 offset:7888
	v_lshlrev_b32_e32 v89, 16, v35
	v_mul_f32_e32 v89, v88, v89
	v_bfe_u32 v90, v89, 16, 1
	v_add3_u32 v89, v89, v90, s3
	ds_write_b16_d16_hi v218, v89 offset:8160
	v_and_b32_e32 v89, 0xffff0000, v35
	v_mul_f32_e32 v89, v88, v89
	v_bfe_u32 v90, v89, 16, 1
	v_add3_u32 v89, v89, v90, s3
	ds_write_b16_d16_hi v218, v89 offset:8432
	v_lshlrev_b32_e32 v89, 16, v40
	v_mul_f32_e32 v89, v88, v89
	v_bfe_u32 v90, v89, 16, 1
	v_add3_u32 v89, v89, v90, s3
	ds_write_b16_d16_hi v218, v89 offset:8704
	v_and_b32_e32 v89, 0xffff0000, v40
	v_mul_f32_e32 v89, v88, v89
	v_bfe_u32 v90, v89, 16, 1
	v_add3_u32 v89, v89, v90, s3
	ds_write_b16_d16_hi v218, v89 offset:8976
	v_lshlrev_b32_e32 v89, 16, v41
	v_mul_f32_e32 v89, v88, v89
	v_bfe_u32 v90, v89, 16, 1
	v_add3_u32 v89, v89, v90, s3
	ds_write_b16_d16_hi v218, v89 offset:9248
	v_and_b32_e32 v89, 0xffff0000, v41
	v_mul_f32_e32 v89, v88, v89
	v_bfe_u32 v90, v89, 16, 1
	v_add3_u32 v89, v89, v90, s3
	ds_write_b16_d16_hi v218, v89 offset:9520
	v_lshlrev_b32_e32 v89, 16, v42
	v_mul_f32_e32 v89, v88, v89
	v_bfe_u32 v90, v89, 16, 1
	v_add3_u32 v89, v89, v90, s3
	ds_write_b16_d16_hi v218, v89 offset:9792
	v_and_b32_e32 v89, 0xffff0000, v42
	v_mul_f32_e32 v89, v88, v89
	v_bfe_u32 v90, v89, 16, 1
	v_add3_u32 v89, v89, v90, s3
	ds_write_b16_d16_hi v218, v89 offset:10064
	v_lshlrev_b32_e32 v89, 16, v43
	v_mul_f32_e32 v89, v88, v89
	v_bfe_u32 v90, v89, 16, 1
	v_add3_u32 v89, v89, v90, s3
	ds_write_b16_d16_hi v218, v89 offset:10336
	v_and_b32_e32 v89, 0xffff0000, v43
	v_mul_f32_e32 v89, v88, v89
	v_bfe_u32 v90, v89, 16, 1
	v_add3_u32 v89, v89, v90, s3
	ds_write_b16_d16_hi v218, v89 offset:10608
	v_lshlrev_b32_e32 v89, 16, v48
	v_mul_f32_e32 v89, v88, v89
	v_bfe_u32 v90, v89, 16, 1
	v_add3_u32 v89, v89, v90, s3
	ds_write_b16_d16_hi v218, v89 offset:10880
	v_and_b32_e32 v89, 0xffff0000, v48
	v_mul_f32_e32 v89, v88, v89
	v_bfe_u32 v90, v89, 16, 1
	v_add3_u32 v89, v89, v90, s3
	ds_write_b16_d16_hi v218, v89 offset:11152
	v_lshlrev_b32_e32 v89, 16, v49
	v_mul_f32_e32 v89, v88, v89
	v_bfe_u32 v90, v89, 16, 1
	v_add3_u32 v89, v89, v90, s3
	ds_write_b16_d16_hi v218, v89 offset:11424
	v_and_b32_e32 v89, 0xffff0000, v49
	v_mul_f32_e32 v89, v88, v89
	v_bfe_u32 v90, v89, 16, 1
	v_add3_u32 v89, v89, v90, s3
	ds_write_b16_d16_hi v218, v89 offset:11696
	v_lshlrev_b32_e32 v89, 16, v50
	v_mul_f32_e32 v89, v88, v89
	v_bfe_u32 v90, v89, 16, 1
	v_add3_u32 v89, v89, v90, s3
	ds_write_b16_d16_hi v218, v89 offset:11968
	v_and_b32_e32 v89, 0xffff0000, v50
	v_mul_f32_e32 v89, v88, v89
	v_bfe_u32 v90, v89, 16, 1
	v_add3_u32 v89, v89, v90, s3
	ds_write_b16_d16_hi v218, v89 offset:12240
	v_lshlrev_b32_e32 v89, 16, v51
	v_mul_f32_e32 v89, v88, v89
	v_bfe_u32 v90, v89, 16, 1
	v_add3_u32 v89, v89, v90, s3
	ds_write_b16_d16_hi v218, v89 offset:12512
	v_and_b32_e32 v89, 0xffff0000, v51
	v_mul_f32_e32 v89, v88, v89
	v_bfe_u32 v90, v89, 16, 1
	v_add3_u32 v89, v89, v90, s3
	ds_write_b16_d16_hi v218, v89 offset:12784
	v_lshlrev_b32_e32 v89, 16, v56
	v_mul_f32_e32 v89, v88, v89
	v_bfe_u32 v90, v89, 16, 1
	v_add3_u32 v89, v89, v90, s3
	ds_write_b16_d16_hi v218, v89 offset:13056
	v_and_b32_e32 v89, 0xffff0000, v56
	v_mul_f32_e32 v89, v88, v89
	v_bfe_u32 v90, v89, 16, 1
	v_add3_u32 v89, v89, v90, s3
	ds_write_b16_d16_hi v218, v89 offset:13328
	v_lshlrev_b32_e32 v89, 16, v57
	v_mul_f32_e32 v89, v88, v89
	v_bfe_u32 v90, v89, 16, 1
	v_add3_u32 v89, v89, v90, s3
	ds_write_b16_d16_hi v218, v89 offset:13600
	v_and_b32_e32 v89, 0xffff0000, v57
	v_mul_f32_e32 v89, v88, v89
	v_bfe_u32 v90, v89, 16, 1
	v_add3_u32 v89, v89, v90, s3
	ds_write_b16_d16_hi v218, v89 offset:13872
	v_lshlrev_b32_e32 v89, 16, v58
	v_mul_f32_e32 v89, v88, v89
	v_bfe_u32 v90, v89, 16, 1
	v_add3_u32 v89, v89, v90, s3
	ds_write_b16_d16_hi v218, v89 offset:14144
	v_and_b32_e32 v89, 0xffff0000, v58
	v_mul_f32_e32 v89, v88, v89
	v_bfe_u32 v90, v89, 16, 1
	v_add3_u32 v89, v89, v90, s3
	ds_write_b16_d16_hi v218, v89 offset:14416
	v_lshlrev_b32_e32 v89, 16, v59
	v_mul_f32_e32 v89, v88, v89
	v_bfe_u32 v90, v89, 16, 1
	v_add3_u32 v89, v89, v90, s3
	ds_write_b16_d16_hi v218, v89 offset:14688
	v_and_b32_e32 v89, 0xffff0000, v59
	v_mul_f32_e32 v89, v88, v89
	v_bfe_u32 v90, v89, 16, 1
	v_add3_u32 v89, v89, v90, s3
	ds_write_b16_d16_hi v218, v89 offset:14960
	v_lshlrev_b32_e32 v89, 16, v64
	v_mul_f32_e32 v89, v88, v89
	v_bfe_u32 v90, v89, 16, 1
	v_add3_u32 v89, v89, v90, s3
	ds_write_b16_d16_hi v218, v89 offset:15232
	v_and_b32_e32 v89, 0xffff0000, v64
	v_mul_f32_e32 v89, v88, v89
	v_bfe_u32 v90, v89, 16, 1
	v_add3_u32 v89, v89, v90, s3
	ds_write_b16_d16_hi v218, v89 offset:15504
	v_lshlrev_b32_e32 v89, 16, v65
	v_mul_f32_e32 v89, v88, v89
	v_bfe_u32 v90, v89, 16, 1
	v_add3_u32 v89, v89, v90, s3
	ds_write_b16_d16_hi v218, v89 offset:15776
	v_and_b32_e32 v89, 0xffff0000, v65
	v_mul_f32_e32 v89, v88, v89
	v_bfe_u32 v90, v89, 16, 1
	v_add3_u32 v89, v89, v90, s3
	ds_write_b16_d16_hi v218, v89 offset:16048
	v_lshlrev_b32_e32 v89, 16, v66
	v_mul_f32_e32 v89, v88, v89
	v_bfe_u32 v90, v89, 16, 1
	v_add3_u32 v89, v89, v90, s3
	ds_write_b16_d16_hi v218, v89 offset:16320
	v_and_b32_e32 v89, 0xffff0000, v66
	v_mul_f32_e32 v89, v88, v89
	v_bfe_u32 v90, v89, 16, 1
	v_add3_u32 v89, v89, v90, s3
	ds_write_b16_d16_hi v218, v89 offset:16592
	v_lshlrev_b32_e32 v89, 16, v67
	v_mul_f32_e32 v89, v88, v89
	v_bfe_u32 v90, v89, 16, 1
	v_add3_u32 v89, v89, v90, s3
	ds_write_b16_d16_hi v218, v89 offset:16864
	v_and_b32_e32 v89, 0xffff0000, v67
	v_mul_f32_e32 v88, v88, v89
	v_bfe_u32 v89, v88, 16, 1
	v_add3_u32 v88, v88, v89, s3
	ds_write_b16_d16_hi v218, v88 offset:17136
	s_cbranch_scc1 .LBB0_715
	v_add_u32_e32 v4, s97, v1
	v_ashrrev_i32_e32 v5, 31, v4
	v_lshlrev_b64 v[4:5], 13, v[4:5]
	v_lshl_add_u64 v[72:73], v[2:3], 0, v[4:5]
	v_lshl_add_u64 v[220:221], v[72:73], 0, v[214:215]
	global_load_dwordx4 v[4:7], v[220:221], off
	global_load_dwordx4 v[12:15], v[220:221], off offset:16
	global_load_dwordx4 v[8:11], v[220:221], off offset:2048
	global_load_dwordx4 v[16:19], v[220:221], off offset:2064
	global_load_dwordx4 v[20:23], v[220:221], off offset:32
	global_load_dwordx4 v[28:31], v[220:221], off offset:48
	global_load_dwordx4 v[24:27], v[220:221], off offset:2080
	global_load_dwordx4 v[32:35], v[220:221], off offset:2096
	global_load_dwordx4 v[36:39], v[220:221], off offset:64
	global_load_dwordx4 v[44:47], v[220:221], off offset:80
	global_load_dwordx4 v[40:43], v[220:221], off offset:2112
	global_load_dwordx4 v[48:51], v[220:221], off offset:2128
	global_load_dwordx4 v[52:55], v[220:221], off offset:96
	global_load_dwordx4 v[60:63], v[220:221], off offset:112
	global_load_dwordx4 v[56:59], v[220:221], off offset:2144
	global_load_dwordx4 v[64:67], v[220:221], off offset:2160
	v_lshl_add_u64 v[72:73], v[140:141], 1, v[72:73]
	v_add_co_u32_e32 v72, vcc, 0x1000, v72
	s_nop 1
	v_addc_co_u32_e32 v73, vcc, 0, v73, vcc
	global_load_dwordx4 v[72:75], v[72:73], off
